# gatepre: residual gate vectors fetched behind the last K-loop barrier (bj=1 into v228..235), epilogue waits for XB+gate before issuing the norm-gain/mods loads (on top of xbpre)
# speedup vs baseline: 1.0041x; 1.0041x over previous
.LBB0_761:
	s_add_i32 vcc_lo, s42, 2
	s_add_u32 s62, s18, s40
	s_addc_u32 s43, s19, s41
	s_add_u32 vcc_hi, s4, s40
	s_addc_u32 s63, s5, s41
	s_add_i32 s95, 0, 0x10000
	s_cmp_eq_u32 s34, s42
	s_cselect_b32 s43, s13, s43
	s_cselect_b32 s42, s12, s62
	v_add_u32_e32 v160, s95, v144
	s_cselect_b32 s63, s37, s63
	s_cselect_b32 s62, s36, vcc_hi
	s_add_i32 vcc_hi, 0, 0x14000
	ds_read_b128 v[148:151], v160
	ds_read_b128 v[152:155], v160 offset:1024
	ds_read_b128 v[156:159], v160 offset:2048
	ds_read_b128 v[166:169], v160 offset:3072
	v_add_u32_e32 v160, vcc_hi, v144
	ds_read_b128 v[170:173], v160
	ds_read_b128 v[174:177], v160 offset:1024
	ds_read_b128 v[178:181], v160 offset:2048
	ds_read_b128 v[182:185], v160 offset:3072
	v_lshl_add_u64 v[160:161], s[18:19], 0, v[140:141]
	s_add_i32 m0, s91, 0xc000
	ds_read_b128 v[186:189], v145
	ds_read_b128 v[190:193], v145 offset:1024
	ds_read_b128 v[194:197], v145 offset:2048
	ds_read_b128 v[198:201], v145 offset:3072
	ds_read_b128 v[202:205], v145 offset:4096
	ds_read_b128 v[206:209], v145 offset:5120
	ds_read_b128 v[210:213], v145 offset:6144
	ds_read_b128 v[214:217], v145 offset:7168
	global_load_lds_dwordx4 v[160:161], off
	v_lshl_add_u64 v[160:161], s[18:19], 0, v[142:143]
	s_add_i32 m0, s91, 0xe000
	s_nop 0
	global_load_lds_dwordx4 v[160:161], off
	s_waitcnt vmcnt(8)
	s_waitcnt lgkmcnt(0)
	s_barrier
	s_setprio 1
	s_waitcnt lgkmcnt(0)
	v_mfma_f32_16x16x32_bf16 v[126:129], v[148:151], v[186:189], v[126:129]
	v_mfma_f32_16x16x32_bf16 v[122:125], v[156:159], v[186:189], v[122:125]
	v_mfma_f32_16x16x32_bf16 v[118:121], v[148:151], v[194:197], v[118:121]
	v_mfma_f32_16x16x32_bf16 v[114:117], v[156:159], v[194:197], v[114:117]
	v_mfma_f32_16x16x32_bf16 v[110:113], v[148:151], v[202:205], v[110:113]
	v_mfma_f32_16x16x32_bf16 v[106:109], v[156:159], v[202:205], v[106:109]
	v_mfma_f32_16x16x32_bf16 v[102:105], v[148:151], v[210:213], v[102:105]
	v_mfma_f32_16x16x32_bf16 v[98:101], v[156:159], v[210:213], v[98:101]
	v_mfma_f32_16x16x32_bf16 v[126:129], v[152:155], v[190:193], v[126:129]
	v_mfma_f32_16x16x32_bf16 v[122:125], v[166:169], v[190:193], v[122:125]
	v_mfma_f32_16x16x32_bf16 v[118:121], v[152:155], v[198:201], v[118:121]
	v_mfma_f32_16x16x32_bf16 v[114:117], v[166:169], v[198:201], v[114:117]
	v_mfma_f32_16x16x32_bf16 v[110:113], v[152:155], v[206:209], v[110:113]
	v_mfma_f32_16x16x32_bf16 v[106:109], v[166:169], v[206:209], v[106:109]
	v_mfma_f32_16x16x32_bf16 v[102:105], v[152:155], v[214:217], v[102:105]
	v_mfma_f32_16x16x32_bf16 v[98:101], v[166:169], v[214:217], v[98:101]
	s_setprio 0
	s_setprio 1
	v_mfma_f32_16x16x32_bf16 v[66:69], v[170:173], v[186:189], v[66:69]
	v_mfma_f32_16x16x32_bf16 v[58:61], v[178:181], v[186:189], v[58:61]
	v_mfma_f32_16x16x32_bf16 v[54:57], v[170:173], v[194:197], v[54:57]
	v_mfma_f32_16x16x32_bf16 v[50:53], v[178:181], v[194:197], v[50:53]
	v_mfma_f32_16x16x32_bf16 v[46:49], v[170:173], v[202:205], v[46:49]
	v_mfma_f32_16x16x32_bf16 v[42:45], v[178:181], v[202:205], v[42:45]
	v_mfma_f32_16x16x32_bf16 v[38:41], v[170:173], v[210:213], v[38:41]
	v_mfma_f32_16x16x32_bf16 v[34:37], v[178:181], v[210:213], v[34:37]
	v_mfma_f32_16x16x32_bf16 v[66:69], v[174:177], v[190:193], v[66:69]
	v_mfma_f32_16x16x32_bf16 v[58:61], v[182:185], v[190:193], v[58:61]
	v_mfma_f32_16x16x32_bf16 v[54:57], v[174:177], v[198:201], v[54:57]
	v_mfma_f32_16x16x32_bf16 v[50:53], v[182:185], v[198:201], v[50:53]
	v_mfma_f32_16x16x32_bf16 v[46:49], v[174:177], v[206:209], v[46:49]
	v_mfma_f32_16x16x32_bf16 v[42:45], v[182:185], v[206:209], v[42:45]
	v_mfma_f32_16x16x32_bf16 v[38:41], v[174:177], v[214:217], v[38:41]
	v_mfma_f32_16x16x32_bf16 v[34:37], v[182:185], v[214:217], v[34:37]
	s_setprio 0
	s_barrier
	s_add_i32 s95, s95, s86
	v_lshl_add_u64 v[160:161], s[62:63], 0, v[0:1]
	s_mov_b32 m0, s95
	ds_read_b128 v[186:189], v145 offset:16384
	ds_read_b128 v[190:193], v145 offset:17408
	ds_read_b128 v[194:197], v145 offset:18432
	ds_read_b128 v[198:201], v145 offset:19456
	ds_read_b128 v[202:205], v145 offset:20480
	ds_read_b128 v[206:209], v145 offset:21504
	ds_read_b128 v[210:213], v145 offset:22528
	ds_read_b128 v[214:217], v145 offset:23552
	global_load_lds_dwordx4 v[160:161], off
	s_add_i32 m0, s95, 0x2000
	v_lshl_add_u64 v[222:223], s[62:63], 0, v[134:135]
	s_add_u32 s62, s62, s87
	s_addc_u32 s63, s63, 0
	s_add_i32 s95, vcc_hi, s86
	global_load_lds_dwordx4 v[222:223], off
	v_lshl_add_u64 v[224:225], s[62:63], 0, v[0:1]
	s_mov_b32 m0, s95
	v_lshl_add_u64 v[226:227], s[62:63], 0, v[134:135]
	global_load_lds_dwordx4 v[224:225], off
	s_add_i32 m0, s95, 0x2000
	v_lshl_add_u64 v[228:229], s[42:43], 0, v[130:131]
	global_load_lds_dwordx4 v[226:227], off
	s_mov_b32 m0, s91
	v_lshl_add_u64 v[230:231], s[42:43], 0, v[132:133]
	global_load_lds_dwordx4 v[228:229], off
	s_mov_b32 m0, s52
	s_nop 0
	global_load_lds_dwordx4 v[230:231], off
	s_waitcnt vmcnt(8)
	s_waitcnt lgkmcnt(0)
	s_barrier
	s_setprio 1
	s_waitcnt lgkmcnt(0)
	v_mfma_f32_16x16x32_bf16 v[94:97], v[148:151], v[186:189], v[94:97]
	v_mfma_f32_16x16x32_bf16 v[90:93], v[156:159], v[186:189], v[90:93]
	v_mfma_f32_16x16x32_bf16 v[86:89], v[148:151], v[194:197], v[86:89]
	v_mfma_f32_16x16x32_bf16 v[82:85], v[156:159], v[194:197], v[82:85]
	v_mfma_f32_16x16x32_bf16 v[78:81], v[148:151], v[202:205], v[78:81]
	v_mfma_f32_16x16x32_bf16 v[74:77], v[156:159], v[202:205], v[74:77]
	v_mfma_f32_16x16x32_bf16 v[70:73], v[148:151], v[210:213], v[70:73]
	v_mfma_f32_16x16x32_bf16 v[62:65], v[156:159], v[210:213], v[62:65]
	v_mfma_f32_16x16x32_bf16 v[94:97], v[152:155], v[190:193], v[94:97]
	v_mfma_f32_16x16x32_bf16 v[90:93], v[166:169], v[190:193], v[90:93]
	v_mfma_f32_16x16x32_bf16 v[86:89], v[152:155], v[198:201], v[86:89]
	v_mfma_f32_16x16x32_bf16 v[82:85], v[166:169], v[198:201], v[82:85]
	v_mfma_f32_16x16x32_bf16 v[78:81], v[152:155], v[206:209], v[78:81]
	v_mfma_f32_16x16x32_bf16 v[74:77], v[166:169], v[206:209], v[74:77]
	v_mfma_f32_16x16x32_bf16 v[70:73], v[152:155], v[214:217], v[70:73]
	v_mfma_f32_16x16x32_bf16 v[62:65], v[166:169], v[214:217], v[62:65]
	s_setprio 0
	s_setprio 1
	v_mfma_f32_16x16x32_bf16 v[30:33], v[170:173], v[186:189], v[30:33]
	v_mfma_f32_16x16x32_bf16 v[26:29], v[178:181], v[186:189], v[26:29]
	v_mfma_f32_16x16x32_bf16 v[22:25], v[170:173], v[194:197], v[22:25]
	v_mfma_f32_16x16x32_bf16 v[18:21], v[178:181], v[194:197], v[18:21]
	v_mfma_f32_16x16x32_bf16 v[14:17], v[170:173], v[202:205], v[14:17]
	v_mfma_f32_16x16x32_bf16 v[10:13], v[178:181], v[202:205], v[10:13]
	v_mfma_f32_16x16x32_bf16 v[6:9], v[170:173], v[210:213], v[6:9]
	v_mfma_f32_16x16x32_bf16 v[2:5], v[178:181], v[210:213], v[2:5]
	v_mfma_f32_16x16x32_bf16 v[30:33], v[174:177], v[190:193], v[30:33]
	v_mfma_f32_16x16x32_bf16 v[26:29], v[182:185], v[190:193], v[26:29]
	v_mfma_f32_16x16x32_bf16 v[22:25], v[174:177], v[198:201], v[22:25]
	v_mfma_f32_16x16x32_bf16 v[18:21], v[182:185], v[198:201], v[18:21]
	v_mfma_f32_16x16x32_bf16 v[14:17], v[174:177], v[206:209], v[14:17]
	v_mfma_f32_16x16x32_bf16 v[10:13], v[182:185], v[206:209], v[10:13]
	v_mfma_f32_16x16x32_bf16 v[6:9], v[174:177], v[214:217], v[6:9]
	v_mfma_f32_16x16x32_bf16 v[2:5], v[182:185], v[214:217], v[2:5]
	s_setprio 0
	s_barrier
	s_add_i32 s62, 0, 0x18000
	v_add_u32_e32 v165, s62, v144
	s_add_i32 s63, 0, 0x1c000
	ds_read_b128 v[148:151], v165
	ds_read_b128 v[152:155], v165 offset:1024
	ds_read_b128 v[156:159], v165 offset:2048
	ds_read_b128 v[166:169], v165 offset:3072
	v_add_u32_e32 v165, s63, v144
	ds_read_b128 v[170:173], v165
	ds_read_b128 v[174:177], v165 offset:1024
	ds_read_b128 v[178:181], v165 offset:2048
	ds_read_b128 v[182:185], v165 offset:3072
	s_add_u32 s42, s42, s87
	s_addc_u32 s43, s43, 0
	s_mov_b32 m0, s53
	v_lshl_add_u64 v[232:233], s[42:43], 0, v[130:131]
	ds_read_b128 v[186:189], v145 offset:32768
	ds_read_b128 v[190:193], v145 offset:33792
	ds_read_b128 v[194:197], v145 offset:34816
	ds_read_b128 v[198:201], v145 offset:35840
	ds_read_b128 v[202:205], v145 offset:36864
	ds_read_b128 v[206:209], v145 offset:37888
	ds_read_b128 v[210:213], v145 offset:38912
	ds_read_b128 v[214:217], v145 offset:39936
	global_load_lds_dwordx4 v[232:233], off
	v_lshl_add_u64 v[232:233], s[42:43], 0, v[132:133]
	s_mov_b32 m0, s50
	s_nop 0
	global_load_lds_dwordx4 v[232:233], off
	s_waitcnt vmcnt(8)
	s_waitcnt lgkmcnt(0)
	s_barrier
	s_setprio 1
	s_waitcnt lgkmcnt(0)
	v_mfma_f32_16x16x32_bf16 v[126:129], v[148:151], v[186:189], v[126:129]
	v_mfma_f32_16x16x32_bf16 v[122:125], v[156:159], v[186:189], v[122:125]
	v_mfma_f32_16x16x32_bf16 v[118:121], v[148:151], v[194:197], v[118:121]
	v_mfma_f32_16x16x32_bf16 v[114:117], v[156:159], v[194:197], v[114:117]
	v_mfma_f32_16x16x32_bf16 v[110:113], v[148:151], v[202:205], v[110:113]
	v_mfma_f32_16x16x32_bf16 v[106:109], v[156:159], v[202:205], v[106:109]
	v_mfma_f32_16x16x32_bf16 v[102:105], v[148:151], v[210:213], v[102:105]
	v_mfma_f32_16x16x32_bf16 v[98:101], v[156:159], v[210:213], v[98:101]
	v_mfma_f32_16x16x32_bf16 v[126:129], v[152:155], v[190:193], v[126:129]
	v_mfma_f32_16x16x32_bf16 v[122:125], v[166:169], v[190:193], v[122:125]
	v_mfma_f32_16x16x32_bf16 v[118:121], v[152:155], v[198:201], v[118:121]
	v_mfma_f32_16x16x32_bf16 v[114:117], v[166:169], v[198:201], v[114:117]
	v_mfma_f32_16x16x32_bf16 v[110:113], v[152:155], v[206:209], v[110:113]
	v_mfma_f32_16x16x32_bf16 v[106:109], v[166:169], v[206:209], v[106:109]
	v_mfma_f32_16x16x32_bf16 v[102:105], v[152:155], v[214:217], v[102:105]
	v_mfma_f32_16x16x32_bf16 v[98:101], v[166:169], v[214:217], v[98:101]
	s_setprio 0
	s_setprio 1
	v_mfma_f32_16x16x32_bf16 v[66:69], v[170:173], v[186:189], v[66:69]
	v_mfma_f32_16x16x32_bf16 v[58:61], v[178:181], v[186:189], v[58:61]
	v_mfma_f32_16x16x32_bf16 v[54:57], v[170:173], v[194:197], v[54:57]
	v_mfma_f32_16x16x32_bf16 v[50:53], v[178:181], v[194:197], v[50:53]
	v_mfma_f32_16x16x32_bf16 v[46:49], v[170:173], v[202:205], v[46:49]
	v_mfma_f32_16x16x32_bf16 v[42:45], v[178:181], v[202:205], v[42:45]
	v_mfma_f32_16x16x32_bf16 v[38:41], v[170:173], v[210:213], v[38:41]
	v_mfma_f32_16x16x32_bf16 v[34:37], v[178:181], v[210:213], v[34:37]
	v_mfma_f32_16x16x32_bf16 v[66:69], v[174:177], v[190:193], v[66:69]
	v_mfma_f32_16x16x32_bf16 v[58:61], v[182:185], v[190:193], v[58:61]
	v_mfma_f32_16x16x32_bf16 v[54:57], v[174:177], v[198:201], v[54:57]
	v_mfma_f32_16x16x32_bf16 v[50:53], v[182:185], v[198:201], v[50:53]
	v_mfma_f32_16x16x32_bf16 v[46:49], v[174:177], v[206:209], v[46:49]
	v_mfma_f32_16x16x32_bf16 v[42:45], v[182:185], v[206:209], v[42:45]
	v_mfma_f32_16x16x32_bf16 v[38:41], v[174:177], v[214:217], v[38:41]
	v_mfma_f32_16x16x32_bf16 v[34:37], v[182:185], v[214:217], v[34:37]
	s_setprio 0
	s_barrier
	s_add_i32 s42, s62, s86
	v_lshl_add_u64 v[160:161], v[160:161], 0, s[76:77]
	s_mov_b32 m0, s42
	ds_read_b128 v[186:189], v145 offset:49152
	ds_read_b128 v[190:193], v145 offset:50176
	ds_read_b128 v[194:197], v145 offset:51200
	ds_read_b128 v[198:201], v145 offset:52224
	ds_read_b128 v[202:205], v145 offset:53248
	ds_read_b128 v[206:209], v145 offset:54272
	ds_read_b128 v[210:213], v145 offset:55296
	ds_read_b128 v[214:217], v145 offset:56320
	global_load_lds_dwordx4 v[160:161], off
	v_lshl_add_u64 v[160:161], v[222:223], 0, s[76:77]
	s_add_i32 m0, s42, 0x2000
	s_add_i32 s42, s63, s86
	global_load_lds_dwordx4 v[160:161], off
	v_lshl_add_u64 v[160:161], v[224:225], 0, s[76:77]
	s_mov_b32 m0, s42
	s_nop 0
	global_load_lds_dwordx4 v[160:161], off
	v_lshl_add_u64 v[160:161], v[226:227], 0, s[76:77]
	s_add_i32 m0, s42, 0x2000
	s_nop 0
	global_load_lds_dwordx4 v[160:161], off
	v_lshl_add_u64 v[160:161], v[228:229], 0, s[76:77]
	s_mov_b32 m0, s35
	s_nop 0
	global_load_lds_dwordx4 v[160:161], off
	v_lshl_add_u64 v[160:161], v[230:231], 0, s[76:77]
	s_mov_b32 m0, s48
	s_nop 0
	global_load_lds_dwordx4 v[160:161], off
	s_waitcnt vmcnt(8)
	s_waitcnt lgkmcnt(0)
	s_barrier
	s_setprio 1
	s_waitcnt lgkmcnt(0)
	v_mfma_f32_16x16x32_bf16 v[94:97], v[148:151], v[186:189], v[94:97]
	v_mfma_f32_16x16x32_bf16 v[90:93], v[156:159], v[186:189], v[90:93]
	v_mfma_f32_16x16x32_bf16 v[86:89], v[148:151], v[194:197], v[86:89]
	v_mfma_f32_16x16x32_bf16 v[82:85], v[156:159], v[194:197], v[82:85]
	v_mfma_f32_16x16x32_bf16 v[78:81], v[148:151], v[202:205], v[78:81]
	v_mfma_f32_16x16x32_bf16 v[74:77], v[156:159], v[202:205], v[74:77]
	v_mfma_f32_16x16x32_bf16 v[70:73], v[148:151], v[210:213], v[70:73]
	v_mfma_f32_16x16x32_bf16 v[62:65], v[156:159], v[210:213], v[62:65]
	v_mfma_f32_16x16x32_bf16 v[94:97], v[152:155], v[190:193], v[94:97]
	v_mfma_f32_16x16x32_bf16 v[90:93], v[166:169], v[190:193], v[90:93]
	v_mfma_f32_16x16x32_bf16 v[86:89], v[152:155], v[198:201], v[86:89]
	v_mfma_f32_16x16x32_bf16 v[82:85], v[166:169], v[198:201], v[82:85]
	v_mfma_f32_16x16x32_bf16 v[78:81], v[152:155], v[206:209], v[78:81]
	v_mfma_f32_16x16x32_bf16 v[74:77], v[166:169], v[206:209], v[74:77]
	v_mfma_f32_16x16x32_bf16 v[70:73], v[152:155], v[214:217], v[70:73]
	v_mfma_f32_16x16x32_bf16 v[62:65], v[166:169], v[214:217], v[62:65]
	s_setprio 0
	s_setprio 1
	v_mfma_f32_16x16x32_bf16 v[30:33], v[170:173], v[186:189], v[30:33]
	v_mfma_f32_16x16x32_bf16 v[26:29], v[178:181], v[186:189], v[26:29]
	v_mfma_f32_16x16x32_bf16 v[22:25], v[170:173], v[194:197], v[22:25]
	v_mfma_f32_16x16x32_bf16 v[18:21], v[178:181], v[194:197], v[18:21]
	v_mfma_f32_16x16x32_bf16 v[14:17], v[170:173], v[202:205], v[14:17]
	v_mfma_f32_16x16x32_bf16 v[10:13], v[178:181], v[202:205], v[10:13]
	v_mfma_f32_16x16x32_bf16 v[6:9], v[170:173], v[210:213], v[6:9]
	v_mfma_f32_16x16x32_bf16 v[2:5], v[178:181], v[210:213], v[2:5]
	v_mfma_f32_16x16x32_bf16 v[30:33], v[174:177], v[190:193], v[30:33]
	v_mfma_f32_16x16x32_bf16 v[26:29], v[182:185], v[190:193], v[26:29]
	v_mfma_f32_16x16x32_bf16 v[22:25], v[174:177], v[198:201], v[22:25]
	v_mfma_f32_16x16x32_bf16 v[18:21], v[182:185], v[198:201], v[18:21]
	v_mfma_f32_16x16x32_bf16 v[14:17], v[174:177], v[206:209], v[14:17]
	v_mfma_f32_16x16x32_bf16 v[10:13], v[182:185], v[206:209], v[10:13]
	v_mfma_f32_16x16x32_bf16 v[6:9], v[174:177], v[214:217], v[6:9]
	v_mfma_f32_16x16x32_bf16 v[2:5], v[182:185], v[214:217], v[2:5]
	s_setprio 0
	s_barrier
	s_add_u32 s40, s40, 0x100
	s_addc_u32 s41, s41, 0
	v_lshl_add_u64 v[142:143], v[142:143], 0, s[74:75]
	v_lshl_add_u64 v[140:141], v[140:141], 0, s[74:75]
	s_cmp_ge_u32 vcc_lo, s34
	s_mov_b32 s42, vcc_lo
	s_cbranch_scc0 .LBB0_761
	s_lshl_b32 s98, s6, 8
	s_add_i32 s98, s98, s80
	v_or_b32_e32 v234, s98, v164
	s_lshl_b32 s98, s28, 8
	s_lshl_b32 s99, s45, 5
	s_or_b32 s98, s98, s99
	v_lshrrev_b32_e32 v236, 1, v163
	v_and_or_b32 v236, v236, 24, s98
	v_lshlrev_b32_e32 v220, 2, v236
	v_lshl_add_u32 v234, v234, 10, v236
	v_lshlrev_b32_e32 v234, 1, v234
	v_mov_b32_e32 v235, 0
	s_add_u32 s98, s96, 0x10000000
	s_addc_u32 s99, s97, 0
	v_lshl_add_u64 v[234:235], s[98:99], 0, v[234:235]
	s_mul_i32 s100, s2, 0x1b000
	s_mul_hi_i32 s101, s2, 0x1b000
	s_add_u32 s100, s100, s96
	s_addc_u32 s101, s101, s97
	s_add_u32 s100, s100, 0x100000
	s_addc_u32 s101, s101, 0
	s_lshl_b32 s98, s71, 2
	s_add_u32 s100, s100, s98
	s_addc_u32 s101, s101, 0
	s_ashr_i32 s98, s6, 5
	s_mul_hi_i32 s99, s98, 0x2400
	s_mulk_i32 s98, 0x2400
	s_lshl_b64 s[98:99], s[98:99], 2
	s_add_u32 s100, s100, s98
	s_addc_u32 s101, s101, s99
	s_add_i32 vcc_lo, s42, 2
	s_add_u32 s62, s18, s40
	s_addc_u32 s43, s19, s41
	s_add_u32 vcc_hi, s4, s40
	s_addc_u32 s63, s5, s41
	s_add_i32 s95, 0, 0x10000
	s_cmp_eq_u32 s34, s42
	s_cselect_b32 s43, s13, s43
	s_cselect_b32 s42, s12, s62
	v_add_u32_e32 v160, s95, v144
	s_cselect_b32 s63, s37, s63
	s_cselect_b32 s62, s36, vcc_hi
	s_add_i32 vcc_hi, 0, 0x14000
	ds_read_b128 v[148:151], v160
	ds_read_b128 v[152:155], v160 offset:1024
	ds_read_b128 v[156:159], v160 offset:2048
	ds_read_b128 v[166:169], v160 offset:3072
	v_add_u32_e32 v160, vcc_hi, v144
	ds_read_b128 v[170:173], v160
	ds_read_b128 v[174:177], v160 offset:1024
	ds_read_b128 v[178:181], v160 offset:2048
	ds_read_b128 v[182:185], v160 offset:3072
	v_lshl_add_u64 v[160:161], s[18:19], 0, v[140:141]
	s_add_i32 m0, s91, 0xc000
	ds_read_b128 v[186:189], v145
	ds_read_b128 v[190:193], v145 offset:1024
	ds_read_b128 v[194:197], v145 offset:2048
	ds_read_b128 v[198:201], v145 offset:3072
	ds_read_b128 v[202:205], v145 offset:4096
	ds_read_b128 v[206:209], v145 offset:5120
	ds_read_b128 v[210:213], v145 offset:6144
	ds_read_b128 v[214:217], v145 offset:7168
	global_load_lds_dwordx4 v[160:161], off
	v_lshl_add_u64 v[160:161], s[18:19], 0, v[142:143]
	s_add_i32 m0, s91, 0xe000
	s_nop 0
	global_load_lds_dwordx4 v[160:161], off
	s_waitcnt vmcnt(8)
	s_waitcnt lgkmcnt(0)
	s_barrier
	s_setprio 1
	s_waitcnt lgkmcnt(0)
	v_mfma_f32_16x16x32_bf16 v[126:129], v[148:151], v[186:189], v[126:129]
	v_mfma_f32_16x16x32_bf16 v[122:125], v[156:159], v[186:189], v[122:125]
	v_mfma_f32_16x16x32_bf16 v[118:121], v[148:151], v[194:197], v[118:121]
	v_mfma_f32_16x16x32_bf16 v[114:117], v[156:159], v[194:197], v[114:117]
	v_mfma_f32_16x16x32_bf16 v[110:113], v[148:151], v[202:205], v[110:113]
	v_mfma_f32_16x16x32_bf16 v[106:109], v[156:159], v[202:205], v[106:109]
	v_mfma_f32_16x16x32_bf16 v[102:105], v[148:151], v[210:213], v[102:105]
	v_mfma_f32_16x16x32_bf16 v[98:101], v[156:159], v[210:213], v[98:101]
	v_mfma_f32_16x16x32_bf16 v[126:129], v[152:155], v[190:193], v[126:129]
	v_mfma_f32_16x16x32_bf16 v[122:125], v[166:169], v[190:193], v[122:125]
	v_mfma_f32_16x16x32_bf16 v[118:121], v[152:155], v[198:201], v[118:121]
	v_mfma_f32_16x16x32_bf16 v[114:117], v[166:169], v[198:201], v[114:117]
	v_mfma_f32_16x16x32_bf16 v[110:113], v[152:155], v[206:209], v[110:113]
	v_mfma_f32_16x16x32_bf16 v[106:109], v[166:169], v[206:209], v[106:109]
	v_mfma_f32_16x16x32_bf16 v[102:105], v[152:155], v[214:217], v[102:105]
	v_mfma_f32_16x16x32_bf16 v[98:101], v[166:169], v[214:217], v[98:101]
	s_setprio 0
	s_setprio 1
	v_mfma_f32_16x16x32_bf16 v[66:69], v[170:173], v[186:189], v[66:69]
	v_mfma_f32_16x16x32_bf16 v[58:61], v[178:181], v[186:189], v[58:61]
	v_mfma_f32_16x16x32_bf16 v[54:57], v[170:173], v[194:197], v[54:57]
	v_mfma_f32_16x16x32_bf16 v[50:53], v[178:181], v[194:197], v[50:53]
	v_mfma_f32_16x16x32_bf16 v[46:49], v[170:173], v[202:205], v[46:49]
	v_mfma_f32_16x16x32_bf16 v[42:45], v[178:181], v[202:205], v[42:45]
	v_mfma_f32_16x16x32_bf16 v[38:41], v[170:173], v[210:213], v[38:41]
	v_mfma_f32_16x16x32_bf16 v[34:37], v[178:181], v[210:213], v[34:37]
	v_mfma_f32_16x16x32_bf16 v[66:69], v[174:177], v[190:193], v[66:69]
	v_mfma_f32_16x16x32_bf16 v[58:61], v[182:185], v[190:193], v[58:61]
	v_mfma_f32_16x16x32_bf16 v[54:57], v[174:177], v[198:201], v[54:57]
	v_mfma_f32_16x16x32_bf16 v[50:53], v[182:185], v[198:201], v[50:53]
	v_mfma_f32_16x16x32_bf16 v[46:49], v[174:177], v[206:209], v[46:49]
	v_mfma_f32_16x16x32_bf16 v[42:45], v[182:185], v[206:209], v[42:45]
	v_mfma_f32_16x16x32_bf16 v[38:41], v[174:177], v[214:217], v[38:41]
	v_mfma_f32_16x16x32_bf16 v[34:37], v[182:185], v[214:217], v[34:37]
	s_setprio 0
	s_barrier
	s_add_i32 s95, s95, s86
	v_lshl_add_u64 v[160:161], s[62:63], 0, v[0:1]
	s_mov_b32 m0, s95
	ds_read_b128 v[186:189], v145 offset:16384
	ds_read_b128 v[190:193], v145 offset:17408
	ds_read_b128 v[194:197], v145 offset:18432
	ds_read_b128 v[198:201], v145 offset:19456
	ds_read_b128 v[202:205], v145 offset:20480
	ds_read_b128 v[206:209], v145 offset:21504
	ds_read_b128 v[210:213], v145 offset:22528
	ds_read_b128 v[214:217], v145 offset:23552
	s_add_i32 m0, s91, 0x10000
	s_nop 0
	global_load_lds_dwordx4 v[234:235], off
	s_add_i32 m0, s95, 0x2000
	v_lshl_add_u64 v[222:223], s[62:63], 0, v[134:135]
	s_add_u32 s62, s62, s87
	s_addc_u32 s63, s63, 0
	s_add_i32 s95, vcc_hi, s86
	s_add_i32 m0, s91, 0x12000
	s_mov_b64 s[98:99], 0x8000
	v_lshl_add_u64 v[236:237], v[234:235], 0, s[98:99]
	global_load_lds_dwordx4 v[236:237], off
	v_lshl_add_u64 v[224:225], s[62:63], 0, v[0:1]
	s_mov_b32 m0, s95
	v_lshl_add_u64 v[226:227], s[62:63], 0, v[134:135]
	s_add_i32 m0, s91, 0x14000
	s_mov_b64 s[98:99], 0x10000
	v_lshl_add_u64 v[236:237], v[234:235], 0, s[98:99]
	global_load_lds_dwordx4 v[236:237], off
	s_add_i32 m0, s95, 0x2000
	v_lshl_add_u64 v[228:229], s[42:43], 0, v[130:131]
	s_add_i32 m0, s91, 0x16000
	s_mov_b64 s[98:99], 0x18000
	v_lshl_add_u64 v[236:237], v[234:235], 0, s[98:99]
	global_load_lds_dwordx4 v[236:237], off
	s_mov_b32 m0, s91
	v_lshl_add_u64 v[230:231], s[42:43], 0, v[132:133]
	s_add_i32 m0, s91, 0x20000
	s_mov_b64 s[98:99], 0x40000
	v_lshl_add_u64 v[236:237], v[234:235], 0, s[98:99]
	global_load_lds_dwordx4 v[236:237], off
	s_mov_b32 m0, s52
	s_nop 0
	s_add_i32 m0, s91, 0x2000
	s_mov_b64 s[98:99], 0x48000
	v_lshl_add_u64 v[236:237], v[234:235], 0, s[98:99]
	global_load_lds_dwordx4 v[236:237], off
	s_add_i32 m0, s91, 0x24000
	s_mov_b64 s[98:99], 0x50000
	v_lshl_add_u64 v[236:237], v[234:235], 0, s[98:99]
	global_load_lds_dwordx4 v[236:237], off
	s_add_i32 m0, s91, 0x26000
	s_mov_b64 s[98:99], 0x58000
	v_lshl_add_u64 v[236:237], v[234:235], 0, s[98:99]
	global_load_lds_dwordx4 v[236:237], off
	s_waitcnt vmcnt(10)
	s_waitcnt lgkmcnt(0)
	s_barrier
	s_setprio 1
	s_waitcnt lgkmcnt(0)
	v_mfma_f32_16x16x32_bf16 v[94:97], v[148:151], v[186:189], v[94:97]
	v_mfma_f32_16x16x32_bf16 v[90:93], v[156:159], v[186:189], v[90:93]
	v_mfma_f32_16x16x32_bf16 v[86:89], v[148:151], v[194:197], v[86:89]
	v_mfma_f32_16x16x32_bf16 v[82:85], v[156:159], v[194:197], v[82:85]
	v_mfma_f32_16x16x32_bf16 v[78:81], v[148:151], v[202:205], v[78:81]
	v_mfma_f32_16x16x32_bf16 v[74:77], v[156:159], v[202:205], v[74:77]
	v_mfma_f32_16x16x32_bf16 v[70:73], v[148:151], v[210:213], v[70:73]
	v_mfma_f32_16x16x32_bf16 v[62:65], v[156:159], v[210:213], v[62:65]
	v_mfma_f32_16x16x32_bf16 v[94:97], v[152:155], v[190:193], v[94:97]
	v_mfma_f32_16x16x32_bf16 v[90:93], v[166:169], v[190:193], v[90:93]
	v_mfma_f32_16x16x32_bf16 v[86:89], v[152:155], v[198:201], v[86:89]
	v_mfma_f32_16x16x32_bf16 v[82:85], v[166:169], v[198:201], v[82:85]
	v_mfma_f32_16x16x32_bf16 v[78:81], v[152:155], v[206:209], v[78:81]
	v_mfma_f32_16x16x32_bf16 v[74:77], v[166:169], v[206:209], v[74:77]
	v_mfma_f32_16x16x32_bf16 v[70:73], v[152:155], v[214:217], v[70:73]
	v_mfma_f32_16x16x32_bf16 v[62:65], v[166:169], v[214:217], v[62:65]
	s_setprio 0
	s_setprio 1
	v_mfma_f32_16x16x32_bf16 v[30:33], v[170:173], v[186:189], v[30:33]
	v_mfma_f32_16x16x32_bf16 v[26:29], v[178:181], v[186:189], v[26:29]
	v_mfma_f32_16x16x32_bf16 v[22:25], v[170:173], v[194:197], v[22:25]
	v_mfma_f32_16x16x32_bf16 v[18:21], v[178:181], v[194:197], v[18:21]
	v_mfma_f32_16x16x32_bf16 v[14:17], v[170:173], v[202:205], v[14:17]
	v_mfma_f32_16x16x32_bf16 v[10:13], v[178:181], v[202:205], v[10:13]
	v_mfma_f32_16x16x32_bf16 v[6:9], v[170:173], v[210:213], v[6:9]
	v_mfma_f32_16x16x32_bf16 v[2:5], v[178:181], v[210:213], v[2:5]
	v_mfma_f32_16x16x32_bf16 v[30:33], v[174:177], v[190:193], v[30:33]
	v_mfma_f32_16x16x32_bf16 v[26:29], v[182:185], v[190:193], v[26:29]
	v_mfma_f32_16x16x32_bf16 v[22:25], v[174:177], v[198:201], v[22:25]
	v_mfma_f32_16x16x32_bf16 v[18:21], v[182:185], v[198:201], v[18:21]
	v_mfma_f32_16x16x32_bf16 v[14:17], v[174:177], v[206:209], v[14:17]
	v_mfma_f32_16x16x32_bf16 v[10:13], v[182:185], v[206:209], v[10:13]
	v_mfma_f32_16x16x32_bf16 v[6:9], v[174:177], v[214:217], v[6:9]
	v_mfma_f32_16x16x32_bf16 v[2:5], v[182:185], v[214:217], v[2:5]
	s_setprio 0
	s_barrier
	s_add_i32 s62, 0, 0x18000
	v_add_u32_e32 v165, s62, v144
	s_add_i32 s63, 0, 0x1c000
	ds_read_b128 v[148:151], v165
	ds_read_b128 v[152:155], v165 offset:1024
	ds_read_b128 v[156:159], v165 offset:2048
	ds_read_b128 v[166:169], v165 offset:3072
	v_add_u32_e32 v165, s63, v144
	ds_read_b128 v[170:173], v165
	ds_read_b128 v[174:177], v165 offset:1024
	ds_read_b128 v[178:181], v165 offset:2048
	ds_read_b128 v[182:185], v165 offset:3072
	s_add_u32 s42, s42, s87
	s_addc_u32 s43, s43, 0
	s_mov_b32 m0, s53
	v_lshl_add_u64 v[232:233], s[42:43], 0, v[130:131]
	ds_read_b128 v[186:189], v145 offset:32768
	ds_read_b128 v[190:193], v145 offset:33792
	ds_read_b128 v[194:197], v145 offset:34816
	ds_read_b128 v[198:201], v145 offset:35840
	ds_read_b128 v[202:205], v145 offset:36864
	ds_read_b128 v[206:209], v145 offset:37888
	ds_read_b128 v[210:213], v145 offset:38912
	ds_read_b128 v[214:217], v145 offset:39936
	s_add_i32 m0, s91, 0x4000
	s_mov_b64 s[98:99], 0x100
	v_lshl_add_u64 v[236:237], v[234:235], 0, s[98:99]
	global_load_lds_dwordx4 v[236:237], off
	v_lshl_add_u64 v[232:233], s[42:43], 0, v[132:133]
	s_mov_b32 m0, s50
	s_nop 0
	s_add_i32 m0, s91, 0x6000
	s_mov_b64 s[98:99], 0x8100
	v_lshl_add_u64 v[236:237], v[234:235], 0, s[98:99]
	global_load_lds_dwordx4 v[236:237], off
	s_waitcnt vmcnt(10)
	s_waitcnt lgkmcnt(0)
	s_barrier
	s_setprio 1
	s_waitcnt lgkmcnt(0)
	v_mfma_f32_16x16x32_bf16 v[126:129], v[148:151], v[186:189], v[126:129]
	v_mfma_f32_16x16x32_bf16 v[122:125], v[156:159], v[186:189], v[122:125]
	v_mfma_f32_16x16x32_bf16 v[118:121], v[148:151], v[194:197], v[118:121]
	v_mfma_f32_16x16x32_bf16 v[114:117], v[156:159], v[194:197], v[114:117]
	v_mfma_f32_16x16x32_bf16 v[110:113], v[148:151], v[202:205], v[110:113]
	v_mfma_f32_16x16x32_bf16 v[106:109], v[156:159], v[202:205], v[106:109]
	v_mfma_f32_16x16x32_bf16 v[102:105], v[148:151], v[210:213], v[102:105]
	v_mfma_f32_16x16x32_bf16 v[98:101], v[156:159], v[210:213], v[98:101]
	v_mfma_f32_16x16x32_bf16 v[126:129], v[152:155], v[190:193], v[126:129]
	v_mfma_f32_16x16x32_bf16 v[122:125], v[166:169], v[190:193], v[122:125]
	v_mfma_f32_16x16x32_bf16 v[118:121], v[152:155], v[198:201], v[118:121]
	v_mfma_f32_16x16x32_bf16 v[114:117], v[166:169], v[198:201], v[114:117]
	v_mfma_f32_16x16x32_bf16 v[110:113], v[152:155], v[206:209], v[110:113]
	v_mfma_f32_16x16x32_bf16 v[106:109], v[166:169], v[206:209], v[106:109]
	v_mfma_f32_16x16x32_bf16 v[102:105], v[152:155], v[214:217], v[102:105]
	v_mfma_f32_16x16x32_bf16 v[98:101], v[166:169], v[214:217], v[98:101]
	s_setprio 0
	s_setprio 1
	v_mfma_f32_16x16x32_bf16 v[66:69], v[170:173], v[186:189], v[66:69]
	v_mfma_f32_16x16x32_bf16 v[58:61], v[178:181], v[186:189], v[58:61]
	v_mfma_f32_16x16x32_bf16 v[54:57], v[170:173], v[194:197], v[54:57]
	v_mfma_f32_16x16x32_bf16 v[50:53], v[178:181], v[194:197], v[50:53]
	v_mfma_f32_16x16x32_bf16 v[46:49], v[170:173], v[202:205], v[46:49]
	v_mfma_f32_16x16x32_bf16 v[42:45], v[178:181], v[202:205], v[42:45]
	v_mfma_f32_16x16x32_bf16 v[38:41], v[170:173], v[210:213], v[38:41]
	v_mfma_f32_16x16x32_bf16 v[34:37], v[178:181], v[210:213], v[34:37]
	v_mfma_f32_16x16x32_bf16 v[66:69], v[174:177], v[190:193], v[66:69]
	v_mfma_f32_16x16x32_bf16 v[58:61], v[182:185], v[190:193], v[58:61]
	v_mfma_f32_16x16x32_bf16 v[54:57], v[174:177], v[198:201], v[54:57]
	v_mfma_f32_16x16x32_bf16 v[50:53], v[182:185], v[198:201], v[50:53]
	v_mfma_f32_16x16x32_bf16 v[46:49], v[174:177], v[206:209], v[46:49]
	v_mfma_f32_16x16x32_bf16 v[42:45], v[182:185], v[206:209], v[42:45]
	v_mfma_f32_16x16x32_bf16 v[38:41], v[174:177], v[214:217], v[38:41]
	v_mfma_f32_16x16x32_bf16 v[34:37], v[182:185], v[214:217], v[34:37]
	s_setprio 0
	s_barrier
	s_add_i32 s42, s62, s86
	v_lshl_add_u64 v[160:161], v[160:161], 0, s[76:77]
	s_mov_b32 m0, s42
	ds_read_b128 v[186:189], v145 offset:49152
	ds_read_b128 v[190:193], v145 offset:50176
	ds_read_b128 v[194:197], v145 offset:51200
	ds_read_b128 v[198:201], v145 offset:52224
	ds_read_b128 v[202:205], v145 offset:53248
	ds_read_b128 v[206:209], v145 offset:54272
	ds_read_b128 v[210:213], v145 offset:55296
	ds_read_b128 v[214:217], v145 offset:56320
	s_add_i32 m0, s91, 0x18000
	s_mov_b64 s[98:99], 0x10100
	v_lshl_add_u64 v[236:237], v[234:235], 0, s[98:99]
	global_load_lds_dwordx4 v[236:237], off
	v_lshl_add_u64 v[160:161], v[222:223], 0, s[76:77]
	s_add_i32 m0, s42, 0x2000
	s_add_i32 s42, s63, s86
	s_add_i32 m0, s91, 0x1a000
	s_mov_b64 s[98:99], 0x18100
	v_lshl_add_u64 v[236:237], v[234:235], 0, s[98:99]
	global_load_lds_dwordx4 v[236:237], off
	v_lshl_add_u64 v[160:161], v[224:225], 0, s[76:77]
	s_mov_b32 m0, s42
	s_nop 0
	s_add_i32 m0, s91, 0x1c000
	s_mov_b64 s[98:99], 0x40100
	v_lshl_add_u64 v[236:237], v[234:235], 0, s[98:99]
	global_load_lds_dwordx4 v[236:237], off
	v_lshl_add_u64 v[160:161], v[226:227], 0, s[76:77]
	s_add_i32 m0, s42, 0x2000
	s_nop 0
	s_add_i32 m0, s91, 0x1e000
	s_mov_b64 s[98:99], 0x48100
	v_lshl_add_u64 v[236:237], v[234:235], 0, s[98:99]
	global_load_lds_dwordx4 v[236:237], off
	v_lshl_add_u64 v[160:161], v[228:229], 0, s[76:77]
	s_mov_b32 m0, s35
	s_nop 0
	s_add_i32 m0, s91, 0x8000
	s_mov_b64 s[98:99], 0x50100
	v_lshl_add_u64 v[236:237], v[234:235], 0, s[98:99]
	global_load_lds_dwordx4 v[236:237], off
	v_lshl_add_u64 v[160:161], v[230:231], 0, s[76:77]
	s_mov_b32 m0, s48
	s_nop 0
	s_add_i32 m0, s91, 0xa000
	s_mov_b64 s[98:99], 0x58100
	v_lshl_add_u64 v[236:237], v[234:235], 0, s[98:99]
	global_load_lds_dwordx4 v[236:237], off
	s_waitcnt vmcnt(16)
	s_waitcnt lgkmcnt(0)
	s_barrier
	global_load_dwordx4 v[134:137], v220, s[100:101] offset:16
	global_load_dwordx4 v[142:145], v220, s[100:101]
	global_load_dwordx4 v[228:231], v220, s[100:101] offset:528
	global_load_dwordx4 v[232:235], v220, s[100:101] offset:512
	s_setprio 1
	s_waitcnt lgkmcnt(0)
	v_mfma_f32_16x16x32_bf16 v[94:97], v[148:151], v[186:189], v[94:97]
	v_mfma_f32_16x16x32_bf16 v[90:93], v[156:159], v[186:189], v[90:93]
	v_mfma_f32_16x16x32_bf16 v[86:89], v[148:151], v[194:197], v[86:89]
	v_mfma_f32_16x16x32_bf16 v[82:85], v[156:159], v[194:197], v[82:85]
	v_mfma_f32_16x16x32_bf16 v[78:81], v[148:151], v[202:205], v[78:81]
	v_mfma_f32_16x16x32_bf16 v[74:77], v[156:159], v[202:205], v[74:77]
	v_mfma_f32_16x16x32_bf16 v[70:73], v[148:151], v[210:213], v[70:73]
	v_mfma_f32_16x16x32_bf16 v[62:65], v[156:159], v[210:213], v[62:65]
	v_mfma_f32_16x16x32_bf16 v[94:97], v[152:155], v[190:193], v[94:97]
	v_mfma_f32_16x16x32_bf16 v[90:93], v[166:169], v[190:193], v[90:93]
	v_mfma_f32_16x16x32_bf16 v[86:89], v[152:155], v[198:201], v[86:89]
	v_mfma_f32_16x16x32_bf16 v[82:85], v[166:169], v[198:201], v[82:85]
	v_mfma_f32_16x16x32_bf16 v[78:81], v[152:155], v[206:209], v[78:81]
	v_mfma_f32_16x16x32_bf16 v[74:77], v[166:169], v[206:209], v[74:77]
	v_mfma_f32_16x16x32_bf16 v[70:73], v[152:155], v[214:217], v[70:73]
	v_mfma_f32_16x16x32_bf16 v[62:65], v[166:169], v[214:217], v[62:65]
	s_setprio 0
	s_setprio 1
	v_mfma_f32_16x16x32_bf16 v[30:33], v[170:173], v[186:189], v[30:33]
	v_mfma_f32_16x16x32_bf16 v[26:29], v[178:181], v[186:189], v[26:29]
	v_mfma_f32_16x16x32_bf16 v[22:25], v[170:173], v[194:197], v[22:25]
	v_mfma_f32_16x16x32_bf16 v[18:21], v[178:181], v[194:197], v[18:21]
	v_mfma_f32_16x16x32_bf16 v[14:17], v[170:173], v[202:205], v[14:17]
	v_mfma_f32_16x16x32_bf16 v[10:13], v[178:181], v[202:205], v[10:13]
	v_mfma_f32_16x16x32_bf16 v[6:9], v[170:173], v[210:213], v[6:9]
	v_mfma_f32_16x16x32_bf16 v[2:5], v[178:181], v[210:213], v[2:5]
	v_mfma_f32_16x16x32_bf16 v[30:33], v[174:177], v[190:193], v[30:33]
	v_mfma_f32_16x16x32_bf16 v[26:29], v[182:185], v[190:193], v[26:29]
	v_mfma_f32_16x16x32_bf16 v[22:25], v[174:177], v[198:201], v[22:25]
	v_mfma_f32_16x16x32_bf16 v[18:21], v[182:185], v[198:201], v[18:21]
	v_mfma_f32_16x16x32_bf16 v[14:17], v[174:177], v[206:209], v[14:17]
	v_mfma_f32_16x16x32_bf16 v[10:13], v[182:185], v[206:209], v[10:13]
	v_mfma_f32_16x16x32_bf16 v[6:9], v[174:177], v[214:217], v[6:9]
	v_mfma_f32_16x16x32_bf16 v[2:5], v[182:185], v[214:217], v[2:5]
	s_setprio 0
	s_barrier
	s_add_u32 s40, s40, 0x100
	s_addc_u32 s41, s41, 0
	v_lshl_add_u64 v[140:141], v[140:141], 0, s[74:75]
	s_cmp_ge_u32 vcc_lo, s51
	s_mov_b32 s42, vcc_lo
	s_and_b64 vcc, exec, s[10:11]
	s_cbranch_vccnz .LBB0_749
	v_mov_b32_e32 v2, 0
	s_mov_b32 s28, s61
	s_mov_b32 s6, s78
	s_mov_b64 s[4:5], s[36:37]
	s_mov_b64 s[18:19], s[12:13]
	s_mov_b32 s49, s7
	v_mov_b32_e32 v3, v2
	v_mov_b32_e32 v4, v2
	v_mov_b32_e32 v5, v2
	v_mov_b32_e32 v6, v2
	v_mov_b32_e32 v7, v2
	v_mov_b32_e32 v8, v2
	v_mov_b32_e32 v9, v2
	v_mov_b32_e32 v10, v2
	v_mov_b32_e32 v11, v2
	v_mov_b32_e32 v12, v2
	v_mov_b32_e32 v13, v2
	v_mov_b32_e32 v14, v2
	v_mov_b32_e32 v15, v2
	v_mov_b32_e32 v16, v2
	v_mov_b32_e32 v17, v2
	v_mov_b32_e32 v18, v2
	v_mov_b32_e32 v19, v2
	v_mov_b32_e32 v20, v2
	v_mov_b32_e32 v21, v2
	v_mov_b32_e32 v22, v2
	v_mov_b32_e32 v23, v2
	v_mov_b32_e32 v24, v2
	v_mov_b32_e32 v25, v2
	v_mov_b32_e32 v26, v2
	v_mov_b32_e32 v27, v2
	v_mov_b32_e32 v28, v2
	v_mov_b32_e32 v29, v2
	v_mov_b32_e32 v30, v2
	v_mov_b32_e32 v31, v2
	v_mov_b32_e32 v32, v2
	v_mov_b32_e32 v33, v2
	v_mov_b32_e32 v62, v2
	v_mov_b32_e32 v63, v2
	v_mov_b32_e32 v64, v2
	v_mov_b32_e32 v65, v2
	v_mov_b32_e32 v70, v2
	v_mov_b32_e32 v71, v2
	v_mov_b32_e32 v72, v2
	v_mov_b32_e32 v73, v2
	v_mov_b32_e32 v74, v2
	v_mov_b32_e32 v75, v2
	v_mov_b32_e32 v76, v2
	v_mov_b32_e32 v77, v2
	v_mov_b32_e32 v78, v2
	v_mov_b32_e32 v79, v2
	v_mov_b32_e32 v80, v2
	v_mov_b32_e32 v81, v2
	v_mov_b32_e32 v82, v2
	v_mov_b32_e32 v83, v2
	v_mov_b32_e32 v84, v2
	v_mov_b32_e32 v85, v2
	v_mov_b32_e32 v86, v2
	v_mov_b32_e32 v87, v2
	v_mov_b32_e32 v88, v2
	v_mov_b32_e32 v89, v2
	v_mov_b32_e32 v90, v2
	v_mov_b32_e32 v91, v2
	v_mov_b32_e32 v92, v2
	v_mov_b32_e32 v93, v2
	v_mov_b32_e32 v94, v2
	v_mov_b32_e32 v95, v2
	v_mov_b32_e32 v96, v2
	v_mov_b32_e32 v97, v2
	v_mov_b32_e32 v34, v2
	v_mov_b32_e32 v35, v2
	v_mov_b32_e32 v36, v2
	v_mov_b32_e32 v37, v2
	v_mov_b32_e32 v38, v2
	v_mov_b32_e32 v39, v2
	v_mov_b32_e32 v40, v2
	v_mov_b32_e32 v41, v2
	v_mov_b32_e32 v42, v2
	v_mov_b32_e32 v43, v2
	v_mov_b32_e32 v44, v2
	v_mov_b32_e32 v45, v2
	v_mov_b32_e32 v46, v2
	v_mov_b32_e32 v47, v2
	v_mov_b32_e32 v48, v2
	v_mov_b32_e32 v49, v2
	v_mov_b32_e32 v50, v2
	v_mov_b32_e32 v51, v2
	v_mov_b32_e32 v52, v2
	v_mov_b32_e32 v53, v2
	v_mov_b32_e32 v54, v2
	v_mov_b32_e32 v55, v2
	v_mov_b32_e32 v56, v2
	v_mov_b32_e32 v57, v2
	v_mov_b32_e32 v58, v2
	v_mov_b32_e32 v59, v2
	v_mov_b32_e32 v60, v2
	v_mov_b32_e32 v61, v2
	v_mov_b32_e32 v66, v2
	v_mov_b32_e32 v67, v2
	v_mov_b32_e32 v68, v2
	v_mov_b32_e32 v69, v2
	v_mov_b32_e32 v98, v2
	v_mov_b32_e32 v99, v2
	v_mov_b32_e32 v100, v2
	v_mov_b32_e32 v101, v2
	v_mov_b32_e32 v102, v2
	v_mov_b32_e32 v103, v2
	v_mov_b32_e32 v104, v2
	v_mov_b32_e32 v105, v2
	v_mov_b32_e32 v106, v2
	v_mov_b32_e32 v107, v2
	v_mov_b32_e32 v108, v2
	v_mov_b32_e32 v109, v2
	v_mov_b32_e32 v110, v2
	v_mov_b32_e32 v111, v2
	v_mov_b32_e32 v112, v2
	v_mov_b32_e32 v113, v2
	v_mov_b32_e32 v114, v2
	v_mov_b32_e32 v115, v2
	v_mov_b32_e32 v116, v2
	v_mov_b32_e32 v117, v2
	v_mov_b32_e32 v118, v2
	v_mov_b32_e32 v119, v2
	v_mov_b32_e32 v120, v2
	v_mov_b32_e32 v121, v2
	v_mov_b32_e32 v122, v2
	v_mov_b32_e32 v123, v2
	v_mov_b32_e32 v124, v2
	v_mov_b32_e32 v125, v2
	v_mov_b32_e32 v126, v2
	v_mov_b32_e32 v127, v2
	v_mov_b32_e32 v128, v2
	v_mov_b32_e32 v129, v2
	s_branch .LBB0_749

.LBB0_782:
	s_mul_i32 s4, s2, 0x1b000
	s_add_u32 s4, s18, s4
	s_mul_hi_i32 s5, s2, 0x1b000
	s_addc_u32 s5, s19, s5
	s_add_u32 s72, s4, 0x100000
	s_addc_u32 s73, s5, 0
	s_lshl_b32 s4, s71, 2
	s_add_u32 s12, s72, s4
	s_addc_u32 s13, s73, 0
	s_ashr_i32 s4, s6, 5
	s_mul_hi_i32 s5, s4, 0x2400
	s_mulk_i32 s4, 0x2400
	s_lshl_b64 s[4:5], s[4:5], 2
	s_add_u32 s12, s12, s4
	s_addc_u32 s13, s13, s5
	v_lshl_add_u64 v[154:155], v[148:149], 2, s[12:13]
	s_waitcnt vmcnt(0)
	v_lshlrev_b32_e32 v216, 2, v148
	global_load_dwordx4 v[176:179], v216, s[36:37] offset:16
	global_load_dwordx4 v[180:183], v216, s[36:37]
	global_load_dwordx4 v[184:187], v216, s[36:37] offset:528
	global_load_dwordx4 v[188:191], v216, s[36:37] offset:512
	s_and_b64 vcc, exec, s[30:31]
	s_cbranch_vccz .Lcab_nomods
	v_readlane_b32 s12, v255, 5
	v_readlane_b32 s13, v255, 4
	s_add_u32 s98, s72, s12
	s_addc_u32 s99, s73, 0
	s_lshl_b32 s13, s13, 2
	s_add_u32 s98, s98, s13
	s_addc_u32 s99, s99, 0
	s_add_u32 s98, s98, s4
	s_addc_u32 s99, s99, s5
	s_add_u32 s100, s98, 0x1000
	s_addc_u32 s101, s99, 0
	global_load_dwordx4 v[192:195], v216, s[100:101] offset:16
	global_load_dwordx4 v[196:199], v216, s[100:101]
	global_load_dwordx4 v[200:203], v216, s[100:101] offset:528
	global_load_dwordx4 v[204:207], v216, s[100:101] offset:512
	global_load_dwordx4 v[208:211], v216, s[98:99]
	global_load_dwordx4 v[212:215], v216, s[98:99] offset:16
	global_load_dwordx4 v[220:223], v216, s[98:99] offset:512
	global_load_dwordx4 v[224:227], v216, s[98:99] offset:528
.Lcab_nomods:
	v_and_b32_e32 v0, 63, v163
	v_lshlrev_b32_e32 v130, 4, v0
	s_mov_b64 s[12:13], -1
	s_and_b64 vcc, exec, s[38:39]
	v_add_u32_e32 v165, s7, v130
	s_lshl_b32 s99, s29, 10
	v_add_u32_e32 v217, s99, v130
	v_add_u32_e32 v236, 0x10000, v217
	v_add_u32_e32 v237, 0x20000, v217
	s_cbranch_vccz .LBB0_784
	ds_read_b128 v[130:133], v236 offset:0
	s_mov_b64 s[12:13], 0
	s_waitcnt lgkmcnt(0)
	v_lshlrev_b32_e32 v138, 16, v130
	v_and_b32_e32 v139, 0xffff0000, v130
	v_lshlrev_b32_e32 v140, 16, v131
	v_and_b32_e32 v141, 0xffff0000, v131
	v_lshlrev_b32_e32 v130, 16, v132
	v_and_b32_e32 v131, 0xffff0000, v132
	v_lshlrev_b32_e32 v132, 16, v133
	v_and_b32_e32 v133, 0xffff0000, v133

.LBB0_812:
	s_and_b64 vcc, exec, s[10:11]
	s_mov_b64 s[12:13], -1
	s_cbranch_vccnz .LBB0_814
	ds_read_b128 v[90:93], v217 offset:8192
	s_waitcnt lgkmcnt(0)
	v_lshlrev_b32_e32 v94, 16, v90
	v_and_b32_e32 v95, 0xffff0000, v90
	v_lshlrev_b32_e32 v96, 16, v91
	v_and_b32_e32 v97, 0xffff0000, v91
	v_lshlrev_b32_e32 v90, 16, v92
	v_and_b32_e32 v91, 0xffff0000, v92
	v_lshlrev_b32_e32 v92, 16, v93
	v_and_b32_e32 v93, 0xffff0000, v93
	s_cbranch_execz .LBB0_815
	s_branch .LBB0_816

.LBB0_830:
	v_mov_b64_e32 v[70:71], v[228:229]
	v_mov_b64_e32 v[72:73], v[230:231]
	v_mov_b64_e32 v[78:79], v[232:233]
	v_mov_b64_e32 v[80:81], v[234:235]
	s_and_b64 vcc, exec, s[10:11]
	s_mov_b64 s[12:13], -1
	s_cbranch_vccnz .LBB0_832
	ds_read_b128 v[62:65], v217 offset:16384
	s_mov_b64 s[12:13], 0
	s_waitcnt lgkmcnt(0)
	v_lshlrev_b32_e32 v74, 16, v62
	v_and_b32_e32 v75, 0xffff0000, v62
	v_lshlrev_b32_e32 v76, 16, v63
	v_and_b32_e32 v77, 0xffff0000, v63
	v_lshlrev_b32_e32 v62, 16, v64
	v_and_b32_e32 v63, 0xffff0000, v64
	v_lshlrev_b32_e32 v64, 16, v65
	v_and_b32_e32 v65, 0xffff0000, v65

.LBB0_836:
	s_and_b64 vcc, exec, s[10:11]
	s_mov_b64 s[12:13], -1
	s_cbranch_vccnz .LBB0_838
	ds_read_b128 v[58:61], v217 offset:24576
	s_waitcnt lgkmcnt(0)
	v_lshlrev_b32_e32 v62, 16, v58
	v_and_b32_e32 v63, 0xffff0000, v58
	v_lshlrev_b32_e32 v64, 16, v59
	v_and_b32_e32 v65, 0xffff0000, v59
	v_lshlrev_b32_e32 v58, 16, v60
	v_and_b32_e32 v59, 0xffff0000, v60
	v_lshlrev_b32_e32 v60, 16, v61
	v_and_b32_e32 v61, 0xffff0000, v61
	s_cbranch_execz .LBB0_839
	s_branch .LBB0_840

.LBB0_866:
	s_and_b64 vcc, exec, s[10:11]
	s_mov_b64 s[12:13], -1
	s_cbranch_vccnz .LBB0_868
	ds_read_b128 v[18:21], v217 offset:32768
	s_waitcnt lgkmcnt(0)
	v_lshlrev_b32_e32 v22, 16, v18
	v_and_b32_e32 v23, 0xffff0000, v18
	v_lshlrev_b32_e32 v24, 16, v19
	v_and_b32_e32 v25, 0xffff0000, v19
	v_lshlrev_b32_e32 v18, 16, v20
	v_and_b32_e32 v19, 0xffff0000, v20
	v_lshlrev_b32_e32 v20, 16, v21
	v_and_b32_e32 v21, 0xffff0000, v21
	s_cbranch_execz .LBB0_869
	s_branch .LBB0_870

.LBB0_872:
	s_and_b64 vcc, exec, s[10:11]
	s_mov_b64 s[10:11], -1
	s_cbranch_vccnz .LBB0_874
	ds_read_b128 v[10:13], v217 offset:40960
	s_waitcnt lgkmcnt(0)
	v_lshlrev_b32_e32 v14, 16, v10
	v_and_b32_e32 v15, 0xffff0000, v10
	v_lshlrev_b32_e32 v16, 16, v11
	v_and_b32_e32 v17, 0xffff0000, v11
	v_lshlrev_b32_e32 v10, 16, v12
	v_and_b32_e32 v11, 0xffff0000, v12
	v_lshlrev_b32_e32 v12, 16, v13
	v_and_b32_e32 v13, 0xffff0000, v13
	s_cbranch_execz .LBB0_875
	s_branch .LBB0_876
